# code placement: 12-byte pad at kernel entry (uniform shift of the instruction stream)
# speedup vs baseline: 1.0036x; 1.0011x over previous
; #define LAS __attribute__((address_space(3)))
; #define KARGS() const CAS Args* KA = kargs()
; __device__ __forceinline__ unsigned xb_add(unsigned* p, unsigned v) { return __hip_atomic_fetch_add(p, v, __ATOMIC_RELAXED, __HIP_MEMORY_SCOPE_AGENT); }
; __device__ __forceinline__ unsigned xb_xcc_id() { return (unsigned)__builtin_amdgcn_s_getreg((3 << 11) | 20) & 0xFu; }
; __device__ __forceinline__ XcdBarrier xcd_barrier_post(unsigned* bar, volatile LAS unsigned* st) {
;     XcdBarrier b; b.bar = bar; b.x = xb_xcc_id(); b.st = st;
;     if (threadIdx.x == 0) (void)xb_add(&bar[XB_XCNT(b.x)], 1u);
;     return b;
; }
; __global__ void __launch_bounds__(512, 2) mega_fwd(Args a) {
;     extern __shared__ __attribute__((aligned(16))) unsigned char lds_raw[];
;     LAS unsigned char* lds = (LAS unsigned char*)lds_raw;
;     cg::grid_group grid = cg::this_grid();
;     if (threadIdx.x < 16) ((LAS unsigned*)(lds + 131072))[threadIdx.x] = 0u;
;     __syncthreads();
;     XcdBarrier xbar; { KARGS(); xbar = xcd_barrier_post((unsigned*)(KA->ws + WS_BAR), (volatile LAS unsigned*)(lds + 131072)); }
_Z8mega_fwd4Args:
	s_nop 0
	s_nop 0
	s_nop 0
	s_add_u32 s4, s0, 0xc0
	v_and_b32_e32 v195, 0x3ff, v0
	s_addc_u32 s5, s1, 0
	v_cmp_gt_u32_e32 vcc, 16, v195
	s_and_saveexec_b64 s[6:7], vcc
	v_lshl_add_u32 v1, v195, 2, 0
	v_add_u32_e32 v1, 0x20000, v1
	v_mov_b32_e32 v2, 0
	ds_write_b32 v1, v2
	s_or_b64 exec, exec, s[6:7]
	s_mov_b64 s[6:7], s[0:1]
	s_load_dwordx2 s[28:29], s[0:1], 0xc0
	s_waitcnt lgkmcnt(0)
	s_barrier
	s_load_dwordx2 s[90:91], s[6:7], 0xb8
	s_getreg_b32 s3, hwreg(HW_REG_XCC_ID, 0, 4)
	v_cmp_eq_u32_e64 s[8:9], 0, v195
	s_waitcnt lgkmcnt(0)
	s_add_u32 s6, s90, 0x32000
	s_addc_u32 s7, s91, 0
	v_writelane_b32 v255, s6, 0
	s_and_b32 s3, s3, 15
	s_nop 0
	v_writelane_b32 v255, s7, 1
	v_writelane_b32 v255, s3, 2
	s_mov_b64 s[6:7], exec
	v_writelane_b32 v255, s8, 3
	s_nop 1
	v_writelane_b32 v255, s9, 4
	s_and_b64 s[8:9], s[6:7], s[8:9]
	s_mov_b64 exec, s[8:9]
	s_cbranch_execz .LBB0_5
	s_mov_b64 s[8:9], exec
	v_mbcnt_lo_u32_b32 v1, s8, 0
	v_mbcnt_hi_u32_b32 v1, s9, v1
	v_cmp_eq_u32_e32 vcc, 0, v1
	s_and_b64 s[10:11], exec, vcc
	s_mov_b64 exec, s[10:11]
	s_cbranch_execz .LBB0_5
	v_readlane_b32 s3, v255, 2
	s_bcnt1_i32_b64 s8, s[8:9]
	s_lshl_b32 s3, s3, 8
	v_mov_b32_e32 v2, s8
	v_readlane_b32 s8, v255, 0
	v_mov_b32_e32 v1, s3
	v_readlane_b32 s9, v255, 1
	s_nop 4
	global_atomic_add v1, v2, s[8:9] offset:1024
